# MLA and diff attention kv loops: LDS staging writes of the next K/V tiles moved from the step tail into the last PV MFMA gaps (counted lgkmcnt waits re-derived)
# speedup vs baseline: 1.0250x; 1.0104x over previous
.LBB0_738:
	v_cvt_pk_bf16_f32 v50, v50, v51
	v_cvt_pk_bf16_f32 v51, v52, v53
	v_cvt_pk_bf16_f32 v52, v54, v182
	v_cvt_pk_bf16_f32 v53, v56, v183
	v_cvt_pk_bf16_f32 v54, v55, v57
	v_cvt_pk_bf16_f32 v55, v58, v59
	v_mfma_f32_32x32x16_bf16 v[82:97], v[198:201], v[50:53], 0
	v_cvt_pk_bf16_f32 v56, v60, v61
	v_cvt_pk_bf16_f32 v57, v62, v63
	v_mfma_f32_32x32x16_bf16 v[2:17], v[170:173], v[50:53], v[2:17]
	ds_read_b64_tr_b16 v[58:59], v221 offset:28672
	ds_read_b64_tr_b16 v[60:61], v221 offset:29184
	v_exp_f32_e32 v62, v34
	v_exp_f32_e32 v63, v35
	v_exp_f32_e32 v64, v36
	v_exp_f32_e32 v65, v37
	v_mfma_f32_32x32x16_bf16 v[18:33], v[166:169], v[50:53], v[18:33]
	ds_read_b64_tr_b16 v[34:35], v221 offset:32768
	ds_read_b64_tr_b16 v[36:37], v221 offset:33280
	v_exp_f32_e32 v50, v38
	v_exp_f32_e32 v51, v39
	v_exp_f32_e32 v52, v40
	v_exp_f32_e32 v41, v41
	v_mfma_f32_32x32x16_bf16 v[82:97], v[198:201], v[54:57], v[82:97]
	v_cvt_pk_bf16_f32 v38, v62, v63
	v_cvt_pk_bf16_f32 v39, v64, v65
	v_cvt_pk_bf16_f32 v40, v50, v51
	v_cvt_pk_bf16_f32 v41, v52, v41
	s_waitcnt lgkmcnt(6)
	v_mfma_f32_32x32x16_bf16 v[2:17], v[178:181], v[54:57], v[2:17]
	ds_read_b64_tr_b16 v[50:51], v221 offset:29696
	ds_read_b64_tr_b16 v[52:53], v221 offset:30208
	v_exp_f32_e32 v62, v42
	v_exp_f32_e32 v63, v43
	v_exp_f32_e32 v64, v44
	v_exp_f32_e32 v65, v45
	s_waitcnt lgkmcnt(6)
	v_mfma_f32_32x32x16_bf16 v[18:33], v[174:177], v[54:57], v[18:33]
	ds_read_b64_tr_b16 v[42:43], v221 offset:33792
	ds_read_b64_tr_b16 v[44:45], v221 offset:34304
	v_exp_f32_e32 v54, v46
	v_exp_f32_e32 v55, v47
	v_exp_f32_e32 v56, v48
	v_exp_f32_e32 v49, v49
	v_mfma_f32_32x32x16_bf16 v[82:97], v[198:201], v[38:41], v[82:97]
	v_cvt_pk_bf16_f32 v46, v62, v63
	v_cvt_pk_bf16_f32 v47, v64, v65
	v_cvt_pk_bf16_f32 v48, v54, v55
	v_cvt_pk_bf16_f32 v49, v56, v49
	s_and_saveexec_b64 s[0:1], s[44:45]
	s_cbranch_execz .LBB0_740
	s_waitcnt vmcnt(2)
	ds_write_b128 v195, v[162:165]
.LBB0_740:
	s_or_b64 exec, exec, s[0:1]
	s_waitcnt lgkmcnt(7)
	v_mfma_f32_32x32x16_bf16 v[2:17], v[58:61], v[38:41], v[2:17]
	s_and_saveexec_b64 s[0:1], s[46:47]
	s_cbranch_execz .LBB0_742
	s_waitcnt vmcnt(1)
	ds_write_b128 v209, v[158:161]
.LBB0_742:
	s_or_b64 exec, exec, s[0:1]
	s_waitcnt lgkmcnt(5)
	v_mfma_f32_32x32x16_bf16 v[18:33], v[34:37], v[38:41], v[18:33]
	v_mfma_f32_32x32x16_bf16 v[82:97], v[198:201], v[46:49], v[82:97]
	s_waitcnt vmcnt(0)
	ds_write_b128 v217, v[154:157] offset:34816
	s_waitcnt lgkmcnt(4)
	v_mfma_f32_32x32x16_bf16 v[2:17], v[50:53], v[46:49], v[2:17]
	s_waitcnt lgkmcnt(2)
	v_mfma_f32_32x32x16_bf16 v[18:33], v[42:45], v[46:49], v[18:33]
	s_and_b64 vcc, exec, s[14:15]
	s_waitcnt lgkmcnt(0)
	s_barrier
	s_cbranch_vccz .LBB0_744
	v_sub_f32_e32 v113, v113, v190
	v_sub_f32_e32 v112, v112, v190
	v_sub_f32_e32 v111, v111, v190
	v_sub_f32_e32 v110, v110, v190
	v_sub_f32_e32 v109, v109, v190
	v_sub_f32_e32 v108, v108, v190
	v_sub_f32_e32 v107, v107, v190
	v_sub_f32_e32 v106, v106, v190
	v_sub_f32_e32 v105, v105, v190
	v_sub_f32_e32 v104, v104, v190
	v_sub_f32_e32 v103, v103, v190
	v_sub_f32_e32 v102, v102, v190
	v_sub_f32_e32 v101, v101, v190
	v_sub_f32_e32 v100, v100, v190
	v_sub_f32_e32 v99, v99, v190
	v_sub_f32_e32 v98, v98, v190
	v_sub_f32_e32 v81, v81, v190
	v_sub_f32_e32 v80, v80, v190
	v_sub_f32_e32 v79, v79, v190
	v_sub_f32_e32 v78, v78, v190
	v_sub_f32_e32 v77, v77, v190
	v_sub_f32_e32 v76, v76, v190
	v_sub_f32_e32 v75, v75, v190
	v_sub_f32_e32 v74, v74, v190
	v_sub_f32_e32 v73, v73, v190
	v_sub_f32_e32 v72, v72, v190
	v_sub_f32_e32 v71, v71, v190
	v_sub_f32_e32 v70, v70, v190
	v_sub_f32_e32 v69, v69, v190
	v_sub_f32_e32 v68, v68, v190
	v_sub_f32_e32 v67, v67, v190
	v_sub_f32_e32 v66, v66, v190

;     ...
;     for (int kt = kt_lo; kt < kt_hi; kt += 2) {
;         FA_STEP(pA0, pA1, pB0, pB1, kt);
;         FA_STEP(pB0, pB1, pA0, pA1, kt + 1);
;     }
.LBB0_749:
	v_cvt_pk_bf16_f32 v108, v96, v97
	v_cvt_pk_bf16_f32 v109, v98, v99
	v_cvt_pk_bf16_f32 v110, v100, v102
	v_cvt_pk_bf16_f32 v111, v103, v186
	v_cvt_pk_bf16_f32 v102, v84, v85
	v_cvt_pk_bf16_f32 v103, v86, v87
	v_mfma_f32_32x32x16_bf16 v[84:99], v[198:201], v[108:111], 0
	v_cvt_pk_bf16_f32 v100, v101, v104
	v_cvt_pk_bf16_f32 v101, v105, v106
	v_mfma_f32_32x32x16_bf16 v[2:17], v[170:173], v[108:111], v[2:17]
	ds_read_b64_tr_b16 v[104:105], v221 offset:36864
	ds_read_b64_tr_b16 v[106:107], v221 offset:37376
	v_exp_f32_e32 v112, v66
	v_exp_f32_e32 v113, v67
	v_exp_f32_e32 v170, v68
	v_exp_f32_e32 v171, v69
	v_mfma_f32_32x32x16_bf16 v[18:33], v[166:169], v[108:111], v[18:33]
	ds_read_b64_tr_b16 v[66:67], v221 offset:40960
	ds_read_b64_tr_b16 v[68:69], v221 offset:41472
	v_exp_f32_e32 v108, v70
	v_exp_f32_e32 v109, v71
	v_exp_f32_e32 v110, v72
	v_exp_f32_e32 v73, v73
	v_mfma_f32_32x32x16_bf16 v[84:99], v[198:201], v[100:103], v[84:99]
	v_cvt_pk_bf16_f32 v70, v112, v113
	v_cvt_pk_bf16_f32 v71, v170, v171
	v_cvt_pk_bf16_f32 v72, v108, v109
	v_cvt_pk_bf16_f32 v73, v110, v73
	s_waitcnt lgkmcnt(6)
	v_mfma_f32_32x32x16_bf16 v[2:17], v[178:181], v[100:103], v[2:17]
	ds_read_b64_tr_b16 v[108:109], v221 offset:37888
	ds_read_b64_tr_b16 v[110:111], v221 offset:38400
	v_exp_f32_e32 v112, v74
	v_exp_f32_e32 v113, v75
	v_exp_f32_e32 v166, v76
	v_exp_f32_e32 v167, v77
	s_waitcnt lgkmcnt(6)
	v_mfma_f32_32x32x16_bf16 v[18:33], v[174:177], v[100:103], v[18:33]
	ds_read_b64_tr_b16 v[74:75], v221 offset:41984
	ds_read_b64_tr_b16 v[76:77], v221 offset:42496
	v_exp_f32_e32 v100, v78
	v_exp_f32_e32 v101, v79
	v_exp_f32_e32 v102, v80
	v_exp_f32_e32 v81, v81
	v_mfma_f32_32x32x16_bf16 v[84:99], v[198:201], v[70:73], v[84:99]
	v_cvt_pk_bf16_f32 v78, v112, v113
	v_cvt_pk_bf16_f32 v79, v166, v167
	v_cvt_pk_bf16_f32 v80, v100, v101
	v_cvt_pk_bf16_f32 v81, v102, v81
	s_and_saveexec_b64 s[0:1], s[44:45]
	s_cbranch_execz .LBB0_751
	s_waitcnt vmcnt(2)
	ds_write_b128 v195, v[162:165] offset:13312
.LBB0_751:
	s_or_b64 exec, exec, s[0:1]
	s_waitcnt lgkmcnt(7)
	v_mfma_f32_32x32x16_bf16 v[2:17], v[104:107], v[70:73], v[2:17]
	s_and_saveexec_b64 s[0:1], s[46:47]
	s_cbranch_execz .LBB0_753
	s_waitcnt vmcnt(1)
	ds_write_b128 v209, v[158:161] offset:13312
.LBB0_753:
	s_or_b64 exec, exec, s[0:1]
	s_waitcnt lgkmcnt(5)
	v_mfma_f32_32x32x16_bf16 v[18:33], v[66:69], v[70:73], v[18:33]
	v_mfma_f32_32x32x16_bf16 v[84:99], v[198:201], v[78:81], v[84:99]
	s_waitcnt vmcnt(0)
	ds_write_b128 v217, v[154:157] offset:26624
	s_waitcnt lgkmcnt(4)
	v_mfma_f32_32x32x16_bf16 v[2:17], v[108:111], v[78:81], v[2:17]
	s_waitcnt lgkmcnt(2)
	v_mfma_f32_32x32x16_bf16 v[18:33], v[74:77], v[78:81], v[18:33]
	v_fmac_f32_e32 v82, v222, v0
	s_mov_b64 s[0:1], 0x80000
	v_cndmask_b32_e64 v191, v223, v83, s[48:49]
	s_cmp_lt_u32 s16, 30
	v_lshl_add_u64 v[214:215], v[214:215], 0, s[0:1]
	s_nop 1
	v_fmac_f32_e32 v84, v82, v218
	s_waitcnt lgkmcnt(0)
	s_barrier
	s_cbranch_scc0 .LBB0_714
	v_mov_b32_e32 v222, v84
	s_andn2_b64 vcc, exec, s[14:15]
	s_cbranch_vccz .LBB0_732
	s_branch .LBB0_733

.LBB0_934:
	v_cvt_pk_bf16_f32 v136, v130, v131
	v_cvt_pk_bf16_f32 v137, v132, v133
	ds_read_b64_tr_b16 v[130:131], v113 offset:18432
	ds_read_b64_tr_b16 v[132:133], v113 offset:18944
	ds_read_b64_tr_b16 v[138:139], v113 offset:22528
	ds_read_b64_tr_b16 v[140:141], v113 offset:23040
	ds_read_b64_tr_b16 v[192:193], v113 offset:26624
	ds_read_b64_tr_b16 v[194:195], v113 offset:27136
	ds_read_b64_tr_b16 v[220:221], v113 offset:30720
	ds_read_b64_tr_b16 v[222:223], v113 offset:31232
	ds_read_b64_tr_b16 v[224:225], v113 offset:19456
	ds_read_b64_tr_b16 v[226:227], v113 offset:19968
	ds_read_b64_tr_b16 v[228:229], v113 offset:23552
	ds_read_b64_tr_b16 v[230:231], v113 offset:24064
	ds_read_b64_tr_b16 v[232:233], v113 offset:27648
	ds_read_b64_tr_b16 v[234:235], v113 offset:28160
	ds_read_b64_tr_b16 v[246:247], v113 offset:31744
	ds_read_b64_tr_b16 v[248:249], v113 offset:32256
	v_cvt_pk_bf16_f32 v134, v126, v127
	v_cvt_pk_bf16_f32 v135, v128, v129
	s_mov_b32 s38, s36
	s_mov_b32 s39, s36
	s_mov_b32 s37, s36
	v_mov_b64_e32 v[198:199], s[38:39]
	v_mov_b64_e32 v[196:197], s[36:37]
	v_cvt_pk_bf16_f32 v200, v118, v119
	v_cvt_pk_bf16_f32 v201, v120, v121
	v_cvt_pk_bf16_f32 v202, v114, v115
	v_cvt_pk_bf16_f32 v203, v116, v117
	v_mfma_f32_32x32x16_bf16 v[114:129], v[196:199], v[134:137], 0
	s_waitcnt lgkmcnt(14)
	v_mfma_f32_32x32x16_bf16 v[64:79], v[130:133], v[134:137], v[64:79]
	ds_read_b64_tr_b16 v[130:131], v113 offset:20480
	ds_read_b64_tr_b16 v[132:133], v113 offset:20992
	s_waitcnt lgkmcnt(14)
	v_mfma_f32_32x32x16_bf16 v[48:63], v[138:141], v[134:137], v[48:63]
	ds_read_b64_tr_b16 v[138:139], v113 offset:24576
	ds_read_b64_tr_b16 v[140:141], v113 offset:25088
	s_waitcnt lgkmcnt(14)
	v_mfma_f32_32x32x16_bf16 v[32:47], v[192:195], v[134:137], v[32:47]
	ds_read_b64_tr_b16 v[192:193], v113 offset:28672
	ds_read_b64_tr_b16 v[194:195], v113 offset:29184
	v_exp_f32_e32 v142, v80
	v_exp_f32_e32 v143, v81
	v_exp_f32_e32 v219, v82
	v_exp_f32_e32 v236, v83
	s_waitcnt lgkmcnt(14)
	v_mfma_f32_32x32x16_bf16 v[16:31], v[220:223], v[134:137], v[16:31]
	ds_read_b64_tr_b16 v[80:81], v113 offset:32768
	ds_read_b64_tr_b16 v[82:83], v113 offset:33280
	v_exp_f32_e32 v134, v84
	v_exp_f32_e32 v135, v85
	v_exp_f32_e32 v136, v86
	v_exp_f32_e32 v87, v87
	v_mfma_f32_32x32x16_bf16 v[114:129], v[196:199], v[200:203], v[114:129]
	v_cvt_pk_bf16_f32 v84, v142, v143
	v_cvt_pk_bf16_f32 v85, v219, v236
	v_cvt_pk_bf16_f32 v86, v134, v135
	v_cvt_pk_bf16_f32 v87, v136, v87
	s_waitcnt lgkmcnt(14)
	v_mfma_f32_32x32x16_bf16 v[64:79], v[224:227], v[200:203], v[64:79]
	ds_read_b64_tr_b16 v[134:135], v113 offset:21504
	ds_read_b64_tr_b16 v[136:137], v113 offset:22016
	s_waitcnt lgkmcnt(14)
	v_mfma_f32_32x32x16_bf16 v[48:63], v[228:231], v[200:203], v[48:63]
	ds_read_b64_tr_b16 v[220:221], v113 offset:25600
	ds_read_b64_tr_b16 v[222:223], v113 offset:26112
	s_waitcnt lgkmcnt(14)
	v_mfma_f32_32x32x16_bf16 v[32:47], v[232:235], v[200:203], v[32:47]
	ds_read_b64_tr_b16 v[224:225], v113 offset:29696
	ds_read_b64_tr_b16 v[226:227], v113 offset:30208
	v_exp_f32_e32 v142, v88
	v_exp_f32_e32 v143, v89
	v_exp_f32_e32 v219, v90
	v_exp_f32_e32 v228, v91
	s_waitcnt lgkmcnt(14)
	v_mfma_f32_32x32x16_bf16 v[16:31], v[246:249], v[200:203], v[16:31]
	ds_read_b64_tr_b16 v[88:89], v113 offset:33792
	ds_read_b64_tr_b16 v[90:91], v113 offset:34304
	v_exp_f32_e32 v200, v92
	v_exp_f32_e32 v201, v93
	v_exp_f32_e32 v202, v94
	v_exp_f32_e32 v95, v95
	v_mfma_f32_32x32x16_bf16 v[114:129], v[196:199], v[84:87], v[114:129]
	v_cvt_pk_bf16_f32 v92, v142, v143
	v_cvt_pk_bf16_f32 v93, v219, v228
	v_cvt_pk_bf16_f32 v94, v200, v201
	v_cvt_pk_bf16_f32 v95, v202, v95
	s_waitcnt lgkmcnt(14)
	v_mfma_f32_32x32x16_bf16 v[64:79], v[130:133], v[84:87], v[64:79]
	s_waitcnt lgkmcnt(12)
	v_mfma_f32_32x32x16_bf16 v[48:63], v[138:141], v[84:87], v[48:63]
	s_waitcnt lgkmcnt(10)
	v_mfma_f32_32x32x16_bf16 v[32:47], v[192:195], v[84:87], v[32:47]
	s_waitcnt lgkmcnt(8)
	v_mfma_f32_32x32x16_bf16 v[16:31], v[80:83], v[84:87], v[16:31]
	v_mfma_f32_32x32x16_bf16 v[114:129], v[196:199], v[92:95], v[114:129]
	s_and_saveexec_b64 s[0:1], s[44:45]
	s_cbranch_execz .LBB0_936
	s_waitcnt vmcnt(2)
	ds_write_b128 v207, v[2:5]
.LBB0_936:
	s_or_b64 exec, exec, s[0:1]
	s_waitcnt lgkmcnt(6)
	v_mfma_f32_32x32x16_bf16 v[64:79], v[134:137], v[92:95], v[64:79]
	s_waitcnt vmcnt(1)
	ds_write_b128 v214, v[6:9] offset:34816
	s_waitcnt lgkmcnt(5)
	v_mfma_f32_32x32x16_bf16 v[48:63], v[220:223], v[92:95], v[48:63]
	s_waitcnt vmcnt(0)
	ds_write_b128 v214, v[10:13] offset:36864
	s_waitcnt lgkmcnt(4)
	v_mfma_f32_32x32x16_bf16 v[32:47], v[224:227], v[92:95], v[32:47]
	s_waitcnt lgkmcnt(2)
	v_mfma_f32_32x32x16_bf16 v[16:31], v[88:91], v[92:95], v[16:31]
	s_add_i32 s0, s31, 0xfffffee2
	s_cmp_lt_u32 s0, 0xfffffea3
	s_waitcnt lgkmcnt(0)
	s_barrier
	s_cbranch_scc1 .LBB0_938
	ds_read2_b32 v[2:3], v216 offset0:64 offset1:65
	ds_read2_b32 v[4:5], v216 offset0:66 offset1:67
	ds_read2_b32 v[6:7], v216 offset0:72 offset1:73
	ds_read2_b32 v[8:9], v216 offset0:74 offset1:75
	ds_read2_b32 v[10:11], v216 offset0:80 offset1:81
	ds_read2_b32 v[12:13], v216 offset0:82 offset1:83
	ds_read2_b32 v[80:81], v216 offset0:88 offset1:89
	ds_read2_b32 v[82:83], v216 offset0:90 offset1:91
	ds_read2_b32 v[84:85], v216 offset0:96 offset1:97
	ds_read2_b32 v[86:87], v216 offset0:98 offset1:99
	ds_read2_b32 v[88:89], v216 offset0:104 offset1:105
	ds_read2_b32 v[90:91], v216 offset0:106 offset1:107
	s_waitcnt lgkmcnt(11)
	v_pk_add_f32 v[144:145], v[144:145], v[2:3]
	s_waitcnt lgkmcnt(5)
	v_pk_add_f32 v[156:157], v[156:157], v[80:81]
	v_pk_add_f32 v[154:155], v[154:155], v[12:13]
	v_pk_add_f32 v[152:153], v[152:153], v[10:11]
	ds_read2_b32 v[2:3], v216 offset0:112 offset1:113
	ds_read2_b32 v[10:11], v216 offset0:114 offset1:115
	ds_read2_b32 v[12:13], v216 offset0:120 offset1:121
	ds_read2_b32 v[80:81], v216 offset0:122 offset1:123
	s_waitcnt lgkmcnt(8)
	v_pk_add_f32 v[158:159], v[158:159], v[82:83]
	v_pk_add_f32 v[150:151], v[150:151], v[8:9]
	v_pk_add_f32 v[148:149], v[148:149], v[6:7]
	v_pk_add_f32 v[146:147], v[146:147], v[4:5]
	s_waitcnt lgkmcnt(7)
	v_pk_add_f32 v[96:97], v[96:97], v[84:85]
	s_waitcnt lgkmcnt(0)
	v_pk_add_f32 v[110:111], v[110:111], v[80:81]
	v_pk_add_f32 v[108:109], v[108:109], v[12:13]
	v_pk_add_f32 v[106:107], v[106:107], v[10:11]
	v_pk_add_f32 v[104:105], v[104:105], v[2:3]
	v_pk_add_f32 v[102:103], v[102:103], v[90:91]
	v_pk_add_f32 v[100:101], v[100:101], v[88:89]
	v_pk_add_f32 v[98:99], v[98:99], v[86:87]

.LBB0_951:
	ds_read_b64_tr_b16 v[192:193], v113 offset:34816
	ds_read_b64_tr_b16 v[194:195], v113 offset:35328
	ds_read_b64_tr_b16 v[196:197], v113 offset:38912
	ds_read_b64_tr_b16 v[198:199], v113 offset:39424
	ds_read_b64_tr_b16 v[200:201], v113 offset:43008
	ds_read_b64_tr_b16 v[202:203], v113 offset:43520
	ds_read_b64_tr_b16 v[220:221], v113 offset:47104
	ds_read_b64_tr_b16 v[222:223], v113 offset:47616
	ds_read_b64_tr_b16 v[224:225], v113 offset:35840
	ds_read_b64_tr_b16 v[226:227], v113 offset:36352
	ds_read_b64_tr_b16 v[228:229], v113 offset:39936
	ds_read_b64_tr_b16 v[230:231], v113 offset:40448
	ds_read_b64_tr_b16 v[232:233], v113 offset:44032
	ds_read_b64_tr_b16 v[234:235], v113 offset:44544
	ds_read_b64_tr_b16 v[246:247], v113 offset:48128
	ds_read_b64_tr_b16 v[248:249], v113 offset:48640
	v_cvt_pk_bf16_f32 v124, v144, v145
	v_cvt_pk_bf16_f32 v125, v146, v147
	v_cvt_pk_bf16_f32 v126, v148, v149
	v_cvt_pk_bf16_f32 v127, v150, v151
	s_mov_b32 s38, s36
	s_mov_b32 s39, s36
	s_mov_b32 s37, s36
	v_mov_b64_e32 v[244:245], s[38:39]
	v_mov_b64_e32 v[242:243], s[36:37]
	v_cvt_pk_bf16_f32 v120, v120, v121
	v_cvt_pk_bf16_f32 v121, v122, v123
	v_mfma_f32_32x32x16_bf16 v[144:159], v[242:245], v[124:127], 0
	v_cvt_pk_bf16_f32 v122, v116, v117
	v_cvt_pk_bf16_f32 v123, v118, v119
	s_waitcnt lgkmcnt(14)
	v_mfma_f32_32x32x16_bf16 v[64:79], v[192:195], v[124:127], v[64:79]
	ds_read_b64_tr_b16 v[116:117], v113 offset:36864
	ds_read_b64_tr_b16 v[118:119], v113 offset:37376
	s_waitcnt lgkmcnt(14)
	v_mfma_f32_32x32x16_bf16 v[48:63], v[196:199], v[124:127], v[48:63]
	ds_read_b64_tr_b16 v[192:193], v113 offset:40960
	ds_read_b64_tr_b16 v[194:195], v113 offset:41472
	s_waitcnt lgkmcnt(14)
	v_mfma_f32_32x32x16_bf16 v[32:47], v[200:203], v[124:127], v[32:47]
	ds_read_b64_tr_b16 v[196:197], v113 offset:45056
	ds_read_b64_tr_b16 v[198:199], v113 offset:45568
	v_exp_f32_e32 v200, v96
	v_exp_f32_e32 v201, v97
	v_exp_f32_e32 v202, v98
	v_exp_f32_e32 v203, v99
	s_waitcnt lgkmcnt(14)
	v_mfma_f32_32x32x16_bf16 v[16:31], v[220:223], v[124:127], v[16:31]
	ds_read_b64_tr_b16 v[96:97], v113 offset:49152
	ds_read_b64_tr_b16 v[98:99], v113 offset:49664
	v_exp_f32_e32 v124, v100
	v_exp_f32_e32 v125, v101
	v_exp_f32_e32 v126, v102
	v_exp_f32_e32 v103, v103
	v_mfma_f32_32x32x16_bf16 v[144:159], v[242:245], v[120:123], v[144:159]
	v_cvt_pk_bf16_f32 v100, v200, v201
	v_cvt_pk_bf16_f32 v101, v202, v203
	v_cvt_pk_bf16_f32 v102, v124, v125
	v_cvt_pk_bf16_f32 v103, v126, v103
	s_waitcnt lgkmcnt(14)
	v_mfma_f32_32x32x16_bf16 v[64:79], v[224:227], v[120:123], v[64:79]
	ds_read_b64_tr_b16 v[124:125], v113 offset:37888
	ds_read_b64_tr_b16 v[126:127], v113 offset:38400
	s_waitcnt lgkmcnt(14)
	v_mfma_f32_32x32x16_bf16 v[48:63], v[228:231], v[120:123], v[48:63]
	ds_read_b64_tr_b16 v[200:201], v113 offset:41984
	ds_read_b64_tr_b16 v[202:203], v113 offset:42496
	s_waitcnt lgkmcnt(14)
	v_mfma_f32_32x32x16_bf16 v[32:47], v[232:235], v[120:123], v[32:47]
	ds_read_b64_tr_b16 v[220:221], v113 offset:46080
	ds_read_b64_tr_b16 v[222:223], v113 offset:46592
	v_exp_f32_e32 v219, v104
	v_exp_f32_e32 v224, v105
	v_exp_f32_e32 v225, v106
	v_exp_f32_e32 v226, v107
	s_waitcnt lgkmcnt(14)
	v_mfma_f32_32x32x16_bf16 v[16:31], v[246:249], v[120:123], v[16:31]
	ds_read_b64_tr_b16 v[104:105], v113 offset:50176
	ds_read_b64_tr_b16 v[106:107], v113 offset:50688
	v_exp_f32_e32 v120, v108
	v_exp_f32_e32 v121, v109
	v_exp_f32_e32 v122, v110
	v_exp_f32_e32 v111, v111
	v_mfma_f32_32x32x16_bf16 v[144:159], v[242:245], v[100:103], v[144:159]
	v_cvt_pk_bf16_f32 v108, v219, v224
	v_cvt_pk_bf16_f32 v109, v225, v226
	v_cvt_pk_bf16_f32 v110, v120, v121
	v_cvt_pk_bf16_f32 v111, v122, v111
	s_waitcnt lgkmcnt(14)
	v_mfma_f32_32x32x16_bf16 v[64:79], v[116:119], v[100:103], v[64:79]
	s_waitcnt lgkmcnt(12)
	v_mfma_f32_32x32x16_bf16 v[48:63], v[192:195], v[100:103], v[48:63]
	s_waitcnt lgkmcnt(10)
	v_mfma_f32_32x32x16_bf16 v[32:47], v[196:199], v[100:103], v[32:47]
	s_waitcnt lgkmcnt(8)
	v_mfma_f32_32x32x16_bf16 v[16:31], v[96:99], v[100:103], v[16:31]
	v_mfma_f32_32x32x16_bf16 v[144:159], v[242:245], v[108:111], v[144:159]
	s_and_saveexec_b64 s[0:1], s[44:45]
	s_cbranch_execz .LBB0_953
	s_waitcnt vmcnt(2)
	ds_write_b128 v207, v[2:5] offset:9216
.LBB0_953:
	s_or_b64 exec, exec, s[0:1]
	s_waitcnt lgkmcnt(6)
	v_mfma_f32_32x32x16_bf16 v[64:79], v[124:127], v[108:111], v[64:79]
	s_waitcnt vmcnt(1)
	ds_write_b128 v214, v[6:9] offset:18432
	s_waitcnt lgkmcnt(5)
	v_mfma_f32_32x32x16_bf16 v[48:63], v[200:203], v[108:111], v[48:63]
	s_waitcnt vmcnt(0)
	ds_write_b128 v214, v[10:13] offset:20480
	s_waitcnt lgkmcnt(4)
	v_mfma_f32_32x32x16_bf16 v[32:47], v[220:223], v[108:111], v[32:47]
	s_waitcnt lgkmcnt(2)
	v_mfma_f32_32x32x16_bf16 v[16:31], v[104:107], v[108:111], v[16:31]
	v_fmac_f32_e32 v114, v15, v14
	s_addk_i32 s31, 0x80
	v_fmac_f32_e32 v144, v114, v112
	v_cndmask_b32_e64 v112, v218, v115, s[46:47]
	v_lshl_add_u64 v[212:213], v[212:213], 0, s[94:95]
	s_cmp_lt_u32 s34, 30
	v_add_u32_e32 v216, 0x200, v216
	s_waitcnt lgkmcnt(0)
	s_barrier
	s_cbranch_scc0 .LBB0_955
	s_mov_b32 s4, s34
	v_mov_b32_e32 v15, v144
	s_add_i32 s0, s31, 0xfffffea2
	s_cmp_lt_u32 s0, 0xfffffea3
	s_cbranch_scc0 .LBB0_925
	s_branch .LBB0_920

.LBB0_980:
	v_cvt_pk_bf16_f32 v136, v130, v131
	v_cvt_pk_bf16_f32 v137, v132, v133
	ds_read_b64_tr_b16 v[130:131], v113 offset:18432
	ds_read_b64_tr_b16 v[132:133], v113 offset:18944
	ds_read_b64_tr_b16 v[138:139], v113 offset:22528
	ds_read_b64_tr_b16 v[140:141], v113 offset:23040
	ds_read_b64_tr_b16 v[192:193], v113 offset:26624
	ds_read_b64_tr_b16 v[194:195], v113 offset:27136
	ds_read_b64_tr_b16 v[196:197], v113 offset:30720
	ds_read_b64_tr_b16 v[198:199], v113 offset:31232
	ds_read_b64_tr_b16 v[200:201], v113 offset:19456
	ds_read_b64_tr_b16 v[202:203], v113 offset:19968
	ds_read_b64_tr_b16 v[220:221], v113 offset:23552
	ds_read_b64_tr_b16 v[222:223], v113 offset:24064
	ds_read_b64_tr_b16 v[224:225], v113 offset:27648
	ds_read_b64_tr_b16 v[226:227], v113 offset:28160
	ds_read_b64_tr_b16 v[228:229], v113 offset:31744
	ds_read_b64_tr_b16 v[230:231], v113 offset:32256
	v_cvt_pk_bf16_f32 v134, v126, v127
	v_cvt_pk_bf16_f32 v135, v128, v129
	s_mov_b32 s38, s36
	s_mov_b32 s39, s36
	s_mov_b32 s37, s36
	v_mov_b64_e32 v[234:235], s[38:39]
	v_mov_b64_e32 v[232:233], s[36:37]
	v_cvt_pk_bf16_f32 v242, v118, v119
	v_cvt_pk_bf16_f32 v243, v120, v121
	v_cvt_pk_bf16_f32 v244, v114, v115
	v_cvt_pk_bf16_f32 v245, v116, v117
	v_mfma_f32_32x32x16_bf16 v[114:129], v[232:235], v[134:137], 0
	s_waitcnt lgkmcnt(14)
	v_mfma_f32_32x32x16_bf16 v[64:79], v[130:133], v[134:137], v[64:79]
	ds_read_b64_tr_b16 v[130:131], v113 offset:20480
	ds_read_b64_tr_b16 v[132:133], v113 offset:20992
	s_waitcnt lgkmcnt(14)
	v_mfma_f32_32x32x16_bf16 v[48:63], v[138:141], v[134:137], v[48:63]
	ds_read_b64_tr_b16 v[138:139], v113 offset:24576
	ds_read_b64_tr_b16 v[140:141], v113 offset:25088
	s_waitcnt lgkmcnt(14)
	v_mfma_f32_32x32x16_bf16 v[32:47], v[192:195], v[134:137], v[32:47]
	ds_read_b64_tr_b16 v[192:193], v113 offset:28672
	ds_read_b64_tr_b16 v[194:195], v113 offset:29184
	v_exp_f32_e32 v142, v80
	v_exp_f32_e32 v143, v81
	v_exp_f32_e32 v219, v82
	v_exp_f32_e32 v236, v83
	s_waitcnt lgkmcnt(14)
	v_mfma_f32_32x32x16_bf16 v[16:31], v[196:199], v[134:137], v[16:31]
	ds_read_b64_tr_b16 v[80:81], v113 offset:32768
	ds_read_b64_tr_b16 v[82:83], v113 offset:33280
	v_exp_f32_e32 v134, v84
	v_exp_f32_e32 v135, v85
	v_exp_f32_e32 v136, v86
	v_exp_f32_e32 v87, v87
	v_mfma_f32_32x32x16_bf16 v[114:129], v[232:235], v[242:245], v[114:129]
	v_cvt_pk_bf16_f32 v84, v142, v143
	v_cvt_pk_bf16_f32 v85, v219, v236
	v_cvt_pk_bf16_f32 v86, v134, v135
	v_cvt_pk_bf16_f32 v87, v136, v87
	s_waitcnt lgkmcnt(14)
	v_mfma_f32_32x32x16_bf16 v[64:79], v[200:203], v[242:245], v[64:79]
	ds_read_b64_tr_b16 v[134:135], v113 offset:21504
	ds_read_b64_tr_b16 v[136:137], v113 offset:22016
	s_waitcnt lgkmcnt(14)
	v_mfma_f32_32x32x16_bf16 v[48:63], v[220:223], v[242:245], v[48:63]
	ds_read_b64_tr_b16 v[196:197], v113 offset:25600
	ds_read_b64_tr_b16 v[198:199], v113 offset:26112
	s_waitcnt lgkmcnt(14)
	v_mfma_f32_32x32x16_bf16 v[32:47], v[224:227], v[242:245], v[32:47]
	ds_read_b64_tr_b16 v[200:201], v113 offset:29696
	ds_read_b64_tr_b16 v[202:203], v113 offset:30208
	v_exp_f32_e32 v142, v88
	v_exp_f32_e32 v143, v89
	v_exp_f32_e32 v219, v90
	v_exp_f32_e32 v220, v91
	s_waitcnt lgkmcnt(14)
	v_mfma_f32_32x32x16_bf16 v[16:31], v[228:231], v[242:245], v[16:31]
	ds_read_b64_tr_b16 v[88:89], v113 offset:33792
	ds_read_b64_tr_b16 v[90:91], v113 offset:34304
	v_exp_f32_e32 v221, v92
	v_exp_f32_e32 v222, v93
	v_exp_f32_e32 v223, v94
	v_exp_f32_e32 v95, v95
	v_mfma_f32_32x32x16_bf16 v[114:129], v[232:235], v[84:87], v[114:129]
	v_cvt_pk_bf16_f32 v92, v142, v143
	v_cvt_pk_bf16_f32 v93, v219, v220
	v_cvt_pk_bf16_f32 v94, v221, v222
	v_cvt_pk_bf16_f32 v95, v223, v95
	s_waitcnt lgkmcnt(14)
	v_mfma_f32_32x32x16_bf16 v[64:79], v[130:133], v[84:87], v[64:79]
	s_waitcnt lgkmcnt(12)
	v_mfma_f32_32x32x16_bf16 v[48:63], v[138:141], v[84:87], v[48:63]
	s_waitcnt lgkmcnt(10)
	v_mfma_f32_32x32x16_bf16 v[32:47], v[192:195], v[84:87], v[32:47]
	s_waitcnt lgkmcnt(8)
	v_mfma_f32_32x32x16_bf16 v[16:31], v[80:83], v[84:87], v[16:31]
	v_mfma_f32_32x32x16_bf16 v[114:129], v[232:235], v[92:95], v[114:129]
	s_and_saveexec_b64 s[0:1], s[44:45]
	s_cbranch_execz .LBB0_982
	s_waitcnt vmcnt(2)
	ds_write_b128 v207, v[2:5]
.LBB0_982:
	s_or_b64 exec, exec, s[0:1]
	s_waitcnt lgkmcnt(6)
	v_mfma_f32_32x32x16_bf16 v[64:79], v[134:137], v[92:95], v[64:79]
	s_waitcnt vmcnt(1)
	ds_write_b128 v214, v[6:9] offset:34816
	s_waitcnt lgkmcnt(5)
	v_mfma_f32_32x32x16_bf16 v[48:63], v[196:199], v[92:95], v[48:63]
	s_waitcnt vmcnt(0)
	ds_write_b128 v214, v[10:13] offset:36864
	s_waitcnt lgkmcnt(4)
	v_mfma_f32_32x32x16_bf16 v[32:47], v[200:203], v[92:95], v[32:47]
	s_waitcnt lgkmcnt(2)
	v_mfma_f32_32x32x16_bf16 v[16:31], v[88:91], v[92:95], v[16:31]
	s_add_i32 s0, s16, 0xfffffee2
	s_cmp_lt_u32 s0, 0xfffffea3
	s_waitcnt lgkmcnt(0)
	s_barrier
	s_cbranch_scc1 .LBB0_984
	ds_read2_b32 v[2:3], v216 offset0:64 offset1:65
	ds_read2_b32 v[4:5], v216 offset0:66 offset1:67
	ds_read2_b32 v[6:7], v216 offset0:72 offset1:73
	ds_read2_b32 v[8:9], v216 offset0:74 offset1:75
	ds_read2_b32 v[10:11], v216 offset0:80 offset1:81
	ds_read2_b32 v[12:13], v216 offset0:82 offset1:83
	ds_read2_b32 v[80:81], v216 offset0:88 offset1:89
	ds_read2_b32 v[82:83], v216 offset0:90 offset1:91
	ds_read2_b32 v[84:85], v216 offset0:96 offset1:97
	ds_read2_b32 v[86:87], v216 offset0:98 offset1:99
	ds_read2_b32 v[88:89], v216 offset0:104 offset1:105
	ds_read2_b32 v[90:91], v216 offset0:106 offset1:107
	s_waitcnt lgkmcnt(11)
	v_pk_add_f32 v[144:145], v[144:145], v[2:3]
	s_waitcnt lgkmcnt(5)
	v_pk_add_f32 v[156:157], v[156:157], v[80:81]
	v_pk_add_f32 v[154:155], v[154:155], v[12:13]
	v_pk_add_f32 v[152:153], v[152:153], v[10:11]
	ds_read2_b32 v[2:3], v216 offset0:112 offset1:113
	ds_read2_b32 v[10:11], v216 offset0:114 offset1:115
	ds_read2_b32 v[12:13], v216 offset0:120 offset1:121
	ds_read2_b32 v[80:81], v216 offset0:122 offset1:123
	s_waitcnt lgkmcnt(8)
	v_pk_add_f32 v[158:159], v[158:159], v[82:83]
	v_pk_add_f32 v[150:151], v[150:151], v[8:9]
	v_pk_add_f32 v[148:149], v[148:149], v[6:7]
	v_pk_add_f32 v[146:147], v[146:147], v[4:5]
	s_waitcnt lgkmcnt(7)
	v_pk_add_f32 v[96:97], v[96:97], v[84:85]
	s_waitcnt lgkmcnt(0)
	v_pk_add_f32 v[110:111], v[110:111], v[80:81]
	v_pk_add_f32 v[108:109], v[108:109], v[12:13]
	v_pk_add_f32 v[106:107], v[106:107], v[10:11]
	v_pk_add_f32 v[104:105], v[104:105], v[2:3]
	v_pk_add_f32 v[102:103], v[102:103], v[90:91]
	v_pk_add_f32 v[100:101], v[100:101], v[88:89]
	v_pk_add_f32 v[98:99], v[98:99], v[86:87]

;     ...
;     for (int kt = kt_lo; kt < kt_hi; kt += 2) {
;         FA_STEP(pA0, pA1, pB0, pB1, kt);
;         FA_STEP(pB0, pB1, pA0, pA1, kt + 1);
.LBB0_997:
	ds_read_b64_tr_b16 v[192:193], v113 offset:34816
	ds_read_b64_tr_b16 v[194:195], v113 offset:35328
	ds_read_b64_tr_b16 v[196:197], v113 offset:38912
	ds_read_b64_tr_b16 v[198:199], v113 offset:39424
	ds_read_b64_tr_b16 v[200:201], v113 offset:43008
	ds_read_b64_tr_b16 v[202:203], v113 offset:43520
	ds_read_b64_tr_b16 v[220:221], v113 offset:47104
	ds_read_b64_tr_b16 v[222:223], v113 offset:47616
	ds_read_b64_tr_b16 v[224:225], v113 offset:35840
	ds_read_b64_tr_b16 v[226:227], v113 offset:36352
	ds_read_b64_tr_b16 v[228:229], v113 offset:39936
	ds_read_b64_tr_b16 v[230:231], v113 offset:40448
	ds_read_b64_tr_b16 v[232:233], v113 offset:44032
	ds_read_b64_tr_b16 v[234:235], v113 offset:44544
	ds_read_b64_tr_b16 v[242:243], v113 offset:48128
	ds_read_b64_tr_b16 v[244:245], v113 offset:48640
	v_cvt_pk_bf16_f32 v124, v144, v145
	v_cvt_pk_bf16_f32 v125, v146, v147
	v_cvt_pk_bf16_f32 v126, v148, v149
	v_cvt_pk_bf16_f32 v127, v150, v151
	s_mov_b32 s38, s36
	s_mov_b32 s39, s36
	s_mov_b32 s37, s36
	v_mov_b64_e32 v[248:249], s[38:39]
	v_mov_b64_e32 v[246:247], s[36:37]
	v_cvt_pk_bf16_f32 v120, v120, v121
	v_cvt_pk_bf16_f32 v121, v122, v123
	v_mfma_f32_32x32x16_bf16 v[144:159], v[246:249], v[124:127], 0
	v_cvt_pk_bf16_f32 v122, v116, v117
	v_cvt_pk_bf16_f32 v123, v118, v119
	s_waitcnt lgkmcnt(14)
	v_mfma_f32_32x32x16_bf16 v[64:79], v[192:195], v[124:127], v[64:79]
	ds_read_b64_tr_b16 v[116:117], v113 offset:36864
	ds_read_b64_tr_b16 v[118:119], v113 offset:37376
	s_waitcnt lgkmcnt(14)
	v_mfma_f32_32x32x16_bf16 v[48:63], v[196:199], v[124:127], v[48:63]
	ds_read_b64_tr_b16 v[192:193], v113 offset:40960
	ds_read_b64_tr_b16 v[194:195], v113 offset:41472
	s_waitcnt lgkmcnt(14)
	v_mfma_f32_32x32x16_bf16 v[32:47], v[200:203], v[124:127], v[32:47]
	ds_read_b64_tr_b16 v[196:197], v113 offset:45056
	ds_read_b64_tr_b16 v[198:199], v113 offset:45568
	v_exp_f32_e32 v200, v96
	v_exp_f32_e32 v201, v97
	v_exp_f32_e32 v202, v98
	v_exp_f32_e32 v203, v99
	s_waitcnt lgkmcnt(14)
	v_mfma_f32_32x32x16_bf16 v[16:31], v[220:223], v[124:127], v[16:31]
	ds_read_b64_tr_b16 v[96:97], v113 offset:49152
	ds_read_b64_tr_b16 v[98:99], v113 offset:49664
	v_exp_f32_e32 v124, v100
	v_exp_f32_e32 v125, v101
	v_exp_f32_e32 v126, v102
	v_exp_f32_e32 v103, v103
	v_mfma_f32_32x32x16_bf16 v[144:159], v[246:249], v[120:123], v[144:159]
	v_cvt_pk_bf16_f32 v100, v200, v201
	v_cvt_pk_bf16_f32 v101, v202, v203
	v_cvt_pk_bf16_f32 v102, v124, v125
	v_cvt_pk_bf16_f32 v103, v126, v103
	s_waitcnt lgkmcnt(14)
	v_mfma_f32_32x32x16_bf16 v[64:79], v[224:227], v[120:123], v[64:79]
	ds_read_b64_tr_b16 v[124:125], v113 offset:37888
	ds_read_b64_tr_b16 v[126:127], v113 offset:38400
	s_waitcnt lgkmcnt(14)
	v_mfma_f32_32x32x16_bf16 v[48:63], v[228:231], v[120:123], v[48:63]
	ds_read_b64_tr_b16 v[200:201], v113 offset:41984
	ds_read_b64_tr_b16 v[202:203], v113 offset:42496
	s_waitcnt lgkmcnt(14)
	v_mfma_f32_32x32x16_bf16 v[32:47], v[232:235], v[120:123], v[32:47]
	ds_read_b64_tr_b16 v[220:221], v113 offset:46080
	ds_read_b64_tr_b16 v[222:223], v113 offset:46592
	v_exp_f32_e32 v219, v104
	v_exp_f32_e32 v224, v105
	v_exp_f32_e32 v225, v106
	v_exp_f32_e32 v226, v107
	s_waitcnt lgkmcnt(14)
	v_mfma_f32_32x32x16_bf16 v[16:31], v[242:245], v[120:123], v[16:31]
	ds_read_b64_tr_b16 v[104:105], v113 offset:50176
	ds_read_b64_tr_b16 v[106:107], v113 offset:50688
	v_exp_f32_e32 v120, v108
	v_exp_f32_e32 v121, v109
	v_exp_f32_e32 v122, v110
	v_exp_f32_e32 v111, v111
	v_mfma_f32_32x32x16_bf16 v[144:159], v[246:249], v[100:103], v[144:159]
	v_cvt_pk_bf16_f32 v108, v219, v224
	v_cvt_pk_bf16_f32 v109, v225, v226
	v_cvt_pk_bf16_f32 v110, v120, v121
	v_cvt_pk_bf16_f32 v111, v122, v111
	s_waitcnt lgkmcnt(14)
	v_mfma_f32_32x32x16_bf16 v[64:79], v[116:119], v[100:103], v[64:79]
	s_waitcnt lgkmcnt(12)
	v_mfma_f32_32x32x16_bf16 v[48:63], v[192:195], v[100:103], v[48:63]
	s_waitcnt lgkmcnt(10)
	v_mfma_f32_32x32x16_bf16 v[32:47], v[196:199], v[100:103], v[32:47]
	s_waitcnt lgkmcnt(8)
	v_mfma_f32_32x32x16_bf16 v[16:31], v[96:99], v[100:103], v[16:31]
	v_mfma_f32_32x32x16_bf16 v[144:159], v[246:249], v[108:111], v[144:159]
	s_and_saveexec_b64 s[0:1], s[44:45]
	s_cbranch_execz .LBB0_999
	s_waitcnt vmcnt(2)
	ds_write_b128 v207, v[10:13] offset:9216
.LBB0_999:
	s_or_b64 exec, exec, s[0:1]
	s_waitcnt lgkmcnt(6)
	v_mfma_f32_32x32x16_bf16 v[64:79], v[124:127], v[108:111], v[64:79]
	s_waitcnt vmcnt(1)
	ds_write_b128 v214, v[2:5] offset:18432
	s_waitcnt lgkmcnt(5)
	v_mfma_f32_32x32x16_bf16 v[48:63], v[200:203], v[108:111], v[48:63]
	s_waitcnt vmcnt(0)
	ds_write_b128 v214, v[6:9] offset:20480
	s_waitcnt lgkmcnt(4)
	v_mfma_f32_32x32x16_bf16 v[32:47], v[220:223], v[108:111], v[32:47]
	s_waitcnt lgkmcnt(2)
	v_mfma_f32_32x32x16_bf16 v[16:31], v[104:107], v[108:111], v[16:31]
	v_fmac_f32_e32 v114, v15, v14
	s_addk_i32 s16, 0x80
	v_fmac_f32_e32 v144, v114, v112
	v_cndmask_b32_e64 v112, v218, v115, s[46:47]
	v_lshl_add_u64 v[212:213], v[212:213], 0, s[94:95]
	s_cmp_lt_u32 s17, 30
	v_add_u32_e32 v216, 0x200, v216
	s_waitcnt lgkmcnt(0)
	s_barrier
	s_cbranch_scc0 .LBB0_892
	s_mov_b32 s4, s17
	v_mov_b32_e32 v15, v144
	s_add_i32 s0, s16, 0xfffffea2
	s_cmp_lt_u32 s0, 0xfffffea3
	s_cbranch_scc0 .LBB0_971
	s_branch .LBB0_966
